# attention: S+softmax interleave, K ds_writes hoisted to step top; spatial phase: v-tile and bias loads batched instead of 8 serialized round trips
# speedup vs baseline: 1.0084x; 1.0084x over previous
; #define LAS __attribute__((address_space(3)))
; __device__ __forceinline__ unsigned cvt_pk_bf16(float lo, float hi) { f32x2 v = {lo, hi}; bf16x2_t b = __builtin_convertvector(v, bf16x2_t); return __builtin_bit_cast(unsigned, b); }
; __device__ __forceinline__ float bf_lo(unsigned u) { return __uint_as_float(u << 16); }
; __device__ __forceinline__ float bf_hi(unsigned u) { return __uint_as_float(u & 0xffff0000u); }
; __device__ __forceinline__ void phase_spatial(const Args& a, LAS unsigned char* lds, int j, int nchunks) {
;     ...
;             f32x4 g0 = *(const f32x4*)(lng + g * 256 + lch * 8), g1 = *(const f32x4*)(lng + g * 256 + lch * 8 + 4), b0 = *(const f32x4*)(lnb + g * 256 + lch * 8), b1 = *(const f32x4*)(lnb + g * 256 + lch * 8 + 4);
; #pragma unroll
;             for (int p = 0; p < 8; ++p) { const int row = lrow + 16 * p; const u32x4 w = *(const u32x4*)(Z + (row0 + row) * SGUW + SGUH + g * 256 + lch * 8);
;                 const f32x2 ms = *(const f32x2*)(st + 2 * (row0 + row));
;                 f32x4 x0 = {bf_lo(w.x), bf_hi(w.x), bf_lo(w.y), bf_hi(w.y)}, x1 = {bf_lo(w.z), bf_hi(w.z), bf_lo(w.w), bf_hi(w.w)};
;                 x0 = (x0 - ms.x) * ms.y * g0 + b0; x1 = (x1 - ms.x) * ms.y * g1 + b1;
;                 u32x4 o; o.x = cvt_pk_bf16(x0[0], x0[1]); o.y = cvt_pk_bf16(x0[2], x0[3]); o.z = cvt_pk_bf16(x1[0], x1[1]); o.w = cvt_pk_bf16(x1[2], x1[3]);
;                 *(LAS u32x4*)(vt + (lch >> 2) * 8192 + (row >> 3) * 512 + (row & 7) * 64 + (lch & 3) * 16) = o; }
;     ...
;         for (int pb = 0; pb < 4; ++pb) { const int p = 32 * pb + r32; const float bias = bs[g * 128 + p];
.LBB0_251:
	s_ashr_i32 s12, s8, 3
	s_ashr_i32 s13, s12, 31
	s_lshl_b64 s[12:13], s[12:13], 7
	v_lshl_add_u64 v[196:197], s[12:13], 0, v[66:67]
	s_lshl_b32 s0, s10, 10
	v_lshlrev_b64 v[98:99], 13, v[196:197]
	v_lshl_add_u64 v[6:7], v[70:71], 0, s[0:1]
	v_lshl_add_u64 v[14:15], v[72:73], 0, s[0:1]
	v_lshl_add_u64 v[156:157], s[46:47], 0, v[98:99]
	s_lshl_b32 s0, s10, 9
	v_lshl_add_u64 v[156:157], v[156:157], 0, s[0:1]
	v_lshl_add_u64 v[156:157], v[156:157], 0, v[0:1]
	s_movk_i32 s10, 0x1000
	v_add_co_u32_e32 v156, vcc, s10, v156
	global_load_dwordx4 v[2:5], v[6:7], off offset:16
	global_load_dwordx4 v[10:13], v[6:7], off
	v_addc_co_u32_e32 v157, vcc, 0, v157, vcc
	global_load_dwordx4 v[6:9], v[14:15], off offset:16
	s_nop 0
	global_load_dwordx4 v[14:17], v[14:15], off
	v_lshl_add_u64 v[196:197], v[196:197], 3, s[50:51]
	global_load_dwordx4 v[156:159], v[156:157], off
	v_lshl_or_b32 v147, v114, 2, s0
	global_load_dwordx2 v[196:197], v[196:197], off
	s_add_i32 s8, s8, s3
	s_cmp_ge_i32 s8, s2
	v_lshl_add_u64 v[198:199], s[12:13], 0, v[84:85]
	v_lshlrev_b64 v[100:101], 13, v[198:199]
	v_lshl_add_u64 v[160:161], s[46:47], 0, v[100:101]
	v_lshl_add_u64 v[160:161], v[160:161], 0, s[0:1]
	v_lshl_add_u64 v[160:161], v[160:161], 0, v[0:1]
	v_add_co_u32_e32 v160, vcc, s10, v160
	v_lshl_add_u64 v[198:199], v[198:199], 3, s[50:51]
	s_nop 0
	v_addc_co_u32_e32 v161, vcc, 0, v161, vcc
	global_load_dwordx4 v[160:163], v[160:161], off
	s_nop 0
	global_load_dwordx2 v[198:199], v[198:199], off
	v_lshl_add_u64 v[200:201], s[12:13], 0, v[86:87]
	v_lshlrev_b64 v[102:103], 13, v[200:201]
	v_lshl_add_u64 v[164:165], s[46:47], 0, v[102:103]
	v_lshl_add_u64 v[164:165], v[164:165], 0, s[0:1]
	v_lshl_add_u64 v[164:165], v[164:165], 0, v[0:1]
	v_add_co_u32_e32 v164, vcc, s10, v164
	v_lshl_add_u64 v[200:201], v[200:201], 3, s[50:51]
	s_nop 0
	v_addc_co_u32_e32 v165, vcc, 0, v165, vcc
	global_load_dwordx4 v[164:167], v[164:165], off
	s_nop 0
	global_load_dwordx2 v[200:201], v[200:201], off
	v_lshl_add_u64 v[202:203], s[12:13], 0, v[88:89]
	v_lshlrev_b64 v[104:105], 13, v[202:203]
	v_lshl_add_u64 v[168:169], s[46:47], 0, v[104:105]
	v_lshl_add_u64 v[168:169], v[168:169], 0, s[0:1]
	v_lshl_add_u64 v[168:169], v[168:169], 0, v[0:1]
	v_add_co_u32_e32 v168, vcc, s10, v168
	v_lshl_add_u64 v[202:203], v[202:203], 3, s[50:51]
	s_nop 0
	v_addc_co_u32_e32 v169, vcc, 0, v169, vcc
	global_load_dwordx4 v[168:171], v[168:169], off
	s_nop 0
	global_load_dwordx2 v[202:203], v[202:203], off
	v_lshl_add_u64 v[208:209], s[12:13], 0, v[90:91]
	v_lshlrev_b64 v[106:107], 13, v[208:209]
	v_lshl_add_u64 v[172:173], s[46:47], 0, v[106:107]
	v_lshl_add_u64 v[172:173], v[172:173], 0, s[0:1]
	v_lshl_add_u64 v[172:173], v[172:173], 0, v[0:1]
	v_add_co_u32_e32 v172, vcc, s10, v172
	v_lshl_add_u64 v[208:209], v[208:209], 3, s[50:51]
	s_nop 0
	v_addc_co_u32_e32 v173, vcc, 0, v173, vcc
	global_load_dwordx4 v[172:175], v[172:173], off
	s_nop 0
	global_load_dwordx2 v[208:209], v[208:209], off
	v_lshl_add_u64 v[210:211], s[12:13], 0, v[92:93]
	v_lshlrev_b64 v[108:109], 13, v[210:211]
	v_lshl_add_u64 v[184:185], s[46:47], 0, v[108:109]
	v_lshl_add_u64 v[184:185], v[184:185], 0, s[0:1]
	v_lshl_add_u64 v[184:185], v[184:185], 0, v[0:1]
	v_add_co_u32_e32 v184, vcc, s10, v184
	v_lshl_add_u64 v[210:211], v[210:211], 3, s[50:51]
	s_nop 0
	v_addc_co_u32_e32 v185, vcc, 0, v185, vcc
	global_load_dwordx4 v[184:187], v[184:185], off
	s_nop 0
	global_load_dwordx2 v[210:211], v[210:211], off
	v_lshl_add_u64 v[212:213], s[12:13], 0, v[94:95]
	v_lshlrev_b64 v[110:111], 13, v[212:213]
	v_lshl_add_u64 v[188:189], s[46:47], 0, v[110:111]
	v_lshl_add_u64 v[188:189], v[188:189], 0, s[0:1]
	v_lshl_add_u64 v[188:189], v[188:189], 0, v[0:1]
	v_add_co_u32_e32 v188, vcc, s10, v188
	v_lshl_add_u64 v[212:213], v[212:213], 3, s[50:51]
	s_nop 0
	v_addc_co_u32_e32 v189, vcc, 0, v189, vcc
	global_load_dwordx4 v[188:191], v[188:189], off
	s_nop 0
	global_load_dwordx2 v[212:213], v[212:213], off
	v_lshl_add_u64 v[22:23], s[12:13], 0, v[96:97]
	v_lshlrev_b64 v[112:113], 13, v[22:23]
	v_lshl_add_u64 v[18:19], s[46:47], 0, v[112:113]
	v_lshl_add_u64 v[18:19], v[18:19], 0, s[0:1]
	v_lshl_add_u64 v[18:19], v[18:19], 0, v[0:1]
	v_add_co_u32_e32 v18, vcc, s10, v18
	v_lshl_add_u64 v[22:23], v[22:23], 3, s[50:51]
	s_nop 0
	v_addc_co_u32_e32 v19, vcc, 0, v19, vcc
	global_load_dwordx4 v[18:21], v[18:19], off
	s_nop 0
	global_load_dwordx2 v[22:23], v[22:23], off
	global_load_dword v224, v147, s[6:7]
	global_load_dword v225, v147, s[6:7] offset:128
	global_load_dword v226, v147, s[6:7] offset:256
	global_load_dword v227, v147, s[6:7] offset:384
	s_waitcnt vmcnt(18)
	v_lshlrev_b32_e32 v24, 16, v156
	v_and_b32_e32 v25, 0xffff0000, v156
	v_lshlrev_b32_e32 v156, 16, v157
	v_and_b32_e32 v157, 0xffff0000, v157
	v_lshlrev_b32_e32 v26, 16, v158
	v_and_b32_e32 v27, 0xffff0000, v158
	v_lshlrev_b32_e32 v28, 16, v159
	v_and_b32_e32 v29, 0xffff0000, v159
	v_sub_f32_e32 v157, v157, v196
	v_sub_f32_e32 v156, v156, v196
	v_sub_f32_e32 v159, v25, v196
	v_sub_f32_e32 v158, v24, v196
	v_pk_mul_f32 v[158:159], v[196:197], v[158:159] op_sel:[1,0]
	v_pk_mul_f32 v[156:157], v[196:197], v[156:157] op_sel:[1,0]
	v_sub_f32_e32 v27, v27, v196
	v_pk_fma_f32 v[24:25], v[12:13], v[156:157], v[16:17]
	v_pk_fma_f32 v[156:157], v[10:11], v[158:159], v[14:15]
	v_sub_f32_e32 v159, v29, v196
	v_sub_f32_e32 v158, v28, v196
	v_sub_f32_e32 v26, v26, v196
	v_pk_mul_f32 v[26:27], v[196:197], v[26:27] op_sel:[1,0]
	v_pk_mul_f32 v[158:159], v[196:197], v[158:159] op_sel:[1,0]
	v_cvt_pk_bf16_f32 v156, v156, v157
	v_pk_fma_f32 v[196:197], v[4:5], v[158:159], v[8:9]
	v_pk_fma_f32 v[158:159], v[2:3], v[26:27], v[6:7]
	v_cvt_pk_bf16_f32 v157, v24, v25
	v_cvt_pk_bf16_f32 v158, v158, v159
	v_cvt_pk_bf16_f32 v159, v196, v197
	ds_write_b128 v121, v[156:159]
	s_waitcnt vmcnt(16)
; #define LAS __attribute__((address_space(3)))
; __device__ __forceinline__ unsigned cvt_pk_bf16(float lo, float hi) { f32x2 v = {lo, hi}; bf16x2_t b = __builtin_convertvector(v, bf16x2_t); return __builtin_bit_cast(unsigned, b); }
; __device__ __forceinline__ float bf_lo(unsigned u) { return __uint_as_float(u << 16); }
; __device__ __forceinline__ float bf_hi(unsigned u) { return __uint_as_float(u & 0xffff0000u); }
; __device__ __forceinline__ void phase_spatial(const Args& a, LAS unsigned char* lds, int j, int nchunks) {
;     ...
;             for (int p = 0; p < 8; ++p) { const int row = lrow + 16 * p; const u32x4 w = *(const u32x4*)(Z + (row0 + row) * SGUW + SGUH + g * 256 + lch * 8);
;                 const f32x2 ms = *(const f32x2*)(st + 2 * (row0 + row));
;                 f32x4 x0 = {bf_lo(w.x), bf_hi(w.x), bf_lo(w.y), bf_hi(w.y)}, x1 = {bf_lo(w.z), bf_hi(w.z), bf_lo(w.w), bf_hi(w.w)};
;                 x0 = (x0 - ms.x) * ms.y * g0 + b0; x1 = (x1 - ms.x) * ms.y * g1 + b1;
;                 u32x4 o; o.x = cvt_pk_bf16(x0[0], x0[1]); o.y = cvt_pk_bf16(x0[2], x0[3]); o.z = cvt_pk_bf16(x1[0], x1[1]); o.w = cvt_pk_bf16(x1[2], x1[3]);
;                 *(LAS u32x4*)(vt + (lch >> 2) * 8192 + (row >> 3) * 512 + (row & 7) * 64 + (lch & 3) * 16) = o; }
	v_lshlrev_b32_e32 v24, 16, v160
	v_and_b32_e32 v25, 0xffff0000, v160
	v_lshlrev_b32_e32 v160, 16, v161
	v_and_b32_e32 v161, 0xffff0000, v161
	v_lshlrev_b32_e32 v26, 16, v162
	v_and_b32_e32 v27, 0xffff0000, v162
	v_lshlrev_b32_e32 v28, 16, v163
	v_and_b32_e32 v29, 0xffff0000, v163
	v_sub_f32_e32 v161, v161, v198
	v_sub_f32_e32 v160, v160, v198
	v_sub_f32_e32 v163, v25, v198
	v_sub_f32_e32 v162, v24, v198
	v_pk_mul_f32 v[162:163], v[198:199], v[162:163] op_sel:[1,0]
	v_pk_mul_f32 v[160:161], v[198:199], v[160:161] op_sel:[1,0]
	v_sub_f32_e32 v27, v27, v198
	v_pk_fma_f32 v[24:25], v[12:13], v[160:161], v[16:17]
	v_pk_fma_f32 v[160:161], v[10:11], v[162:163], v[14:15]
	v_sub_f32_e32 v163, v29, v198
	v_sub_f32_e32 v162, v28, v198
	v_sub_f32_e32 v26, v26, v198
	v_pk_mul_f32 v[26:27], v[198:199], v[26:27] op_sel:[1,0]
	v_pk_mul_f32 v[162:163], v[198:199], v[162:163] op_sel:[1,0]
	v_cvt_pk_bf16_f32 v160, v160, v161
	v_pk_fma_f32 v[198:199], v[4:5], v[162:163], v[8:9]
	v_pk_fma_f32 v[162:163], v[2:3], v[26:27], v[6:7]
	v_cvt_pk_bf16_f32 v161, v24, v25
	v_cvt_pk_bf16_f32 v162, v162, v163
	v_cvt_pk_bf16_f32 v163, v198, v199
	ds_write_b128 v122, v[160:163]
	s_waitcnt vmcnt(14)
	v_lshlrev_b32_e32 v24, 16, v164
	v_and_b32_e32 v25, 0xffff0000, v164
	v_lshlrev_b32_e32 v164, 16, v165
	v_and_b32_e32 v165, 0xffff0000, v165
	v_lshlrev_b32_e32 v26, 16, v166
	v_and_b32_e32 v27, 0xffff0000, v166
	v_lshlrev_b32_e32 v28, 16, v167
	v_and_b32_e32 v29, 0xffff0000, v167
	v_sub_f32_e32 v165, v165, v200
	v_sub_f32_e32 v164, v164, v200
	v_sub_f32_e32 v167, v25, v200
	v_sub_f32_e32 v166, v24, v200
	v_pk_mul_f32 v[166:167], v[200:201], v[166:167] op_sel:[1,0]
	v_pk_mul_f32 v[164:165], v[200:201], v[164:165] op_sel:[1,0]
	v_sub_f32_e32 v27, v27, v200
	v_pk_fma_f32 v[24:25], v[12:13], v[164:165], v[16:17]
	v_pk_fma_f32 v[164:165], v[10:11], v[166:167], v[14:15]
	v_sub_f32_e32 v167, v29, v200
	v_sub_f32_e32 v166, v28, v200
	v_sub_f32_e32 v26, v26, v200
	v_pk_mul_f32 v[26:27], v[200:201], v[26:27] op_sel:[1,0]
	v_pk_mul_f32 v[166:167], v[200:201], v[166:167] op_sel:[1,0]
	v_cvt_pk_bf16_f32 v164, v164, v165
	v_pk_fma_f32 v[200:201], v[4:5], v[166:167], v[8:9]
	v_pk_fma_f32 v[166:167], v[2:3], v[26:27], v[6:7]
	v_cvt_pk_bf16_f32 v165, v24, v25
	v_cvt_pk_bf16_f32 v166, v166, v167
	v_cvt_pk_bf16_f32 v167, v200, v201
	ds_write_b128 v123, v[164:167]
	s_waitcnt vmcnt(12)
	v_lshlrev_b32_e32 v24, 16, v168
	v_and_b32_e32 v25, 0xffff0000, v168
	v_lshlrev_b32_e32 v168, 16, v169
	v_and_b32_e32 v169, 0xffff0000, v169
	v_lshlrev_b32_e32 v26, 16, v170
	v_and_b32_e32 v27, 0xffff0000, v170
	v_lshlrev_b32_e32 v28, 16, v171
	v_and_b32_e32 v29, 0xffff0000, v171
	v_sub_f32_e32 v169, v169, v202
	v_sub_f32_e32 v168, v168, v202
	v_sub_f32_e32 v171, v25, v202
	v_sub_f32_e32 v170, v24, v202
	v_pk_mul_f32 v[170:171], v[202:203], v[170:171] op_sel:[1,0]
	v_pk_mul_f32 v[168:169], v[202:203], v[168:169] op_sel:[1,0]
	v_sub_f32_e32 v27, v27, v202
	v_pk_fma_f32 v[24:25], v[12:13], v[168:169], v[16:17]
	v_pk_fma_f32 v[168:169], v[10:11], v[170:171], v[14:15]
	v_sub_f32_e32 v171, v29, v202
	v_sub_f32_e32 v170, v28, v202
	v_sub_f32_e32 v26, v26, v202
	v_pk_mul_f32 v[26:27], v[202:203], v[26:27] op_sel:[1,0]
	v_pk_mul_f32 v[170:171], v[202:203], v[170:171] op_sel:[1,0]
	v_cvt_pk_bf16_f32 v168, v168, v169
	v_pk_fma_f32 v[202:203], v[4:5], v[170:171], v[8:9]
	v_pk_fma_f32 v[170:171], v[2:3], v[26:27], v[6:7]
	v_cvt_pk_bf16_f32 v169, v24, v25
	v_cvt_pk_bf16_f32 v170, v170, v171
	v_cvt_pk_bf16_f32 v171, v202, v203
	ds_write_b128 v124, v[168:171]
	s_waitcnt vmcnt(10)
	v_lshlrev_b32_e32 v24, 16, v172
	v_and_b32_e32 v25, 0xffff0000, v172
	v_lshlrev_b32_e32 v172, 16, v173
	v_and_b32_e32 v173, 0xffff0000, v173
	v_lshlrev_b32_e32 v26, 16, v174
	v_and_b32_e32 v27, 0xffff0000, v174
	v_lshlrev_b32_e32 v28, 16, v175
	v_and_b32_e32 v29, 0xffff0000, v175
	v_sub_f32_e32 v173, v173, v208
	v_sub_f32_e32 v172, v172, v208
	v_sub_f32_e32 v175, v25, v208
	v_sub_f32_e32 v174, v24, v208
	v_pk_mul_f32 v[174:175], v[208:209], v[174:175] op_sel:[1,0]
	v_pk_mul_f32 v[172:173], v[208:209], v[172:173] op_sel:[1,0]
	v_sub_f32_e32 v27, v27, v208
	v_pk_fma_f32 v[24:25], v[12:13], v[172:173], v[16:17]
	v_pk_fma_f32 v[172:173], v[10:11], v[174:175], v[14:15]
	v_sub_f32_e32 v175, v29, v208
	v_sub_f32_e32 v174, v28, v208
	v_sub_f32_e32 v26, v26, v208
	v_pk_mul_f32 v[26:27], v[208:209], v[26:27] op_sel:[1,0]
	v_pk_mul_f32 v[174:175], v[208:209], v[174:175] op_sel:[1,0]
	v_cvt_pk_bf16_f32 v172, v172, v173
	v_pk_fma_f32 v[208:209], v[4:5], v[174:175], v[8:9]
	v_pk_fma_f32 v[174:175], v[2:3], v[26:27], v[6:7]
	v_cvt_pk_bf16_f32 v173, v24, v25
	v_cvt_pk_bf16_f32 v174, v174, v175
	v_cvt_pk_bf16_f32 v175, v208, v209
	ds_write_b128 v125, v[172:175]
	s_waitcnt vmcnt(8)
	v_lshlrev_b32_e32 v24, 16, v184
	v_and_b32_e32 v25, 0xffff0000, v184
	v_lshlrev_b32_e32 v184, 16, v185
	v_and_b32_e32 v185, 0xffff0000, v185
	v_lshlrev_b32_e32 v26, 16, v186
	v_and_b32_e32 v27, 0xffff0000, v186
	v_lshlrev_b32_e32 v28, 16, v187
	v_and_b32_e32 v29, 0xffff0000, v187
	v_sub_f32_e32 v185, v185, v210
	v_sub_f32_e32 v184, v184, v210
	v_sub_f32_e32 v187, v25, v210
	v_sub_f32_e32 v186, v24, v210
	v_pk_mul_f32 v[186:187], v[210:211], v[186:187] op_sel:[1,0]
	v_pk_mul_f32 v[184:185], v[210:211], v[184:185] op_sel:[1,0]
	v_sub_f32_e32 v27, v27, v210
	v_pk_fma_f32 v[24:25], v[12:13], v[184:185], v[16:17]
	v_pk_fma_f32 v[184:185], v[10:11], v[186:187], v[14:15]
	v_sub_f32_e32 v187, v29, v210
	v_sub_f32_e32 v186, v28, v210
	v_sub_f32_e32 v26, v26, v210
	v_pk_mul_f32 v[26:27], v[210:211], v[26:27] op_sel:[1,0]
	v_pk_mul_f32 v[186:187], v[210:211], v[186:187] op_sel:[1,0]
	v_cvt_pk_bf16_f32 v184, v184, v185
	v_pk_fma_f32 v[210:211], v[4:5], v[186:187], v[8:9]
	v_pk_fma_f32 v[186:187], v[2:3], v[26:27], v[6:7]
	v_cvt_pk_bf16_f32 v185, v24, v25
	v_cvt_pk_bf16_f32 v186, v186, v187
	v_cvt_pk_bf16_f32 v187, v210, v211
	ds_write_b128 v126, v[184:187]
	s_waitcnt vmcnt(6)
; #define LAS __attribute__((address_space(3)))
; __device__ __forceinline__ unsigned cvt_pk_bf16(float lo, float hi) { f32x2 v = {lo, hi}; bf16x2_t b = __builtin_convertvector(v, bf16x2_t); return __builtin_bit_cast(unsigned, b); }
; __device__ __forceinline__ float bf_lo(unsigned u) { return __uint_as_float(u << 16); }
; __device__ __forceinline__ float bf_hi(unsigned u) { return __uint_as_float(u & 0xffff0000u); }
; __device__ __forceinline__ void phase_spatial(const Args& a, LAS unsigned char* lds, int j, int nchunks) {
;     ...
;             for (int p = 0; p < 8; ++p) { const int row = lrow + 16 * p; const u32x4 w = *(const u32x4*)(Z + (row0 + row) * SGUW + SGUH + g * 256 + lch * 8);
;                 const f32x2 ms = *(const f32x2*)(st + 2 * (row0 + row));
;                 f32x4 x0 = {bf_lo(w.x), bf_hi(w.x), bf_lo(w.y), bf_hi(w.y)}, x1 = {bf_lo(w.z), bf_hi(w.z), bf_lo(w.w), bf_hi(w.w)};
;                 x0 = (x0 - ms.x) * ms.y * g0 + b0; x1 = (x1 - ms.x) * ms.y * g1 + b1;
;                 u32x4 o; o.x = cvt_pk_bf16(x0[0], x0[1]); o.y = cvt_pk_bf16(x0[2], x0[3]); o.z = cvt_pk_bf16(x1[0], x1[1]); o.w = cvt_pk_bf16(x1[2], x1[3]);
;                 *(LAS u32x4*)(vt + (lch >> 2) * 8192 + (row >> 3) * 512 + (row & 7) * 64 + (lch & 3) * 16) = o; }
;     ...
;         __syncthreads();
;         f32x16 acc[4];
; #pragma unroll
;         for (int pb = 0; pb < 4; ++pb)
; #pragma unroll
;             for (int i = 0; i < 16; ++i) acc[pb][i] = 0.f;
;         const int vb = wid * 8192 + ((lane >> 4) & 1) * 32 + (lane & 3) * 8 + ((lane & 15) >> 2) * 64;
; #pragma unroll
;         for (int ks = 0; ks < 8; ++ks) {
;             const s16x4 lo = __builtin_bit_cast(s16x4, __builtin_amdgcn_ds_read_tr16_b64_v4i16((LAS s16x4*)(vt + vb + (2 * ks + hi) * 512)));
;             const s16x4 hh = __builtin_bit_cast(s16x4, __builtin_amdgcn_ds_read_tr16_b64_v4i16((LAS s16x4*)(vt + vb + (2 * ks + hi) * 512 + 256)));
;             const bf16x8 vf = __builtin_shufflevector(lo, hh, 0, 1, 2, 3, 4, 5, 6, 7);
; #pragma unroll
;             for (int pb = 0; pb < 4; ++pb) { const int row = 32 * pb + r32; const bf16x8 wf = *(const LAS bf16x8*)(wl + row * 256 + (((2 * ks + hi) ^ (row & 15)) << 4));
;                 acc[pb] = __builtin_amdgcn_mfma_f32_32x32x16_bf16(vf, wf, acc[pb], 0, 0, 0); }
;         }
	v_lshlrev_b32_e32 v24, 16, v188
	v_and_b32_e32 v25, 0xffff0000, v188
	v_lshlrev_b32_e32 v188, 16, v189
	v_and_b32_e32 v189, 0xffff0000, v189
	v_lshlrev_b32_e32 v26, 16, v190
	v_and_b32_e32 v27, 0xffff0000, v190
	v_lshlrev_b32_e32 v28, 16, v191
	v_and_b32_e32 v29, 0xffff0000, v191
	v_sub_f32_e32 v189, v189, v212
	v_sub_f32_e32 v188, v188, v212
	v_sub_f32_e32 v191, v25, v212
	v_sub_f32_e32 v190, v24, v212
	v_pk_mul_f32 v[190:191], v[212:213], v[190:191] op_sel:[1,0]
	v_pk_mul_f32 v[188:189], v[212:213], v[188:189] op_sel:[1,0]
	v_sub_f32_e32 v27, v27, v212
	v_pk_fma_f32 v[24:25], v[12:13], v[188:189], v[16:17]
	v_pk_fma_f32 v[188:189], v[10:11], v[190:191], v[14:15]
	v_sub_f32_e32 v191, v29, v212
	v_sub_f32_e32 v190, v28, v212
	v_sub_f32_e32 v26, v26, v212
	v_pk_mul_f32 v[26:27], v[212:213], v[26:27] op_sel:[1,0]
	v_pk_mul_f32 v[190:191], v[212:213], v[190:191] op_sel:[1,0]
	v_cvt_pk_bf16_f32 v188, v188, v189
	v_pk_fma_f32 v[212:213], v[4:5], v[190:191], v[8:9]
	v_pk_fma_f32 v[190:191], v[2:3], v[26:27], v[6:7]
	v_cvt_pk_bf16_f32 v189, v24, v25
	v_cvt_pk_bf16_f32 v190, v190, v191
	v_cvt_pk_bf16_f32 v191, v212, v213
	ds_write_b128 v127, v[188:191]
	s_waitcnt vmcnt(4)
	v_lshlrev_b32_e32 v24, 16, v18
	v_and_b32_e32 v25, 0xffff0000, v18
	v_lshlrev_b32_e32 v18, 16, v19
	v_and_b32_e32 v19, 0xffff0000, v19
	v_lshlrev_b32_e32 v26, 16, v20
	v_and_b32_e32 v27, 0xffff0000, v20
	v_lshlrev_b32_e32 v28, 16, v21
	v_and_b32_e32 v29, 0xffff0000, v21
	v_sub_f32_e32 v19, v19, v22
	v_sub_f32_e32 v18, v18, v22
	v_sub_f32_e32 v21, v25, v22
	v_sub_f32_e32 v20, v24, v22
	v_pk_mul_f32 v[20:21], v[22:23], v[20:21] op_sel:[1,0]
	v_pk_mul_f32 v[18:19], v[22:23], v[18:19] op_sel:[1,0]
	v_pk_fma_f32 v[10:11], v[10:11], v[20:21], v[14:15]
	v_pk_fma_f32 v[12:13], v[12:13], v[18:19], v[16:17]
	v_sub_f32_e32 v15, v29, v22
	v_sub_f32_e32 v14, v28, v22
	v_sub_f32_e32 v17, v27, v22
	v_sub_f32_e32 v16, v26, v22
	v_pk_mul_f32 v[16:17], v[22:23], v[16:17] op_sel:[1,0]
	v_pk_mul_f32 v[14:15], v[22:23], v[14:15] op_sel:[1,0]
	s_nop 0
	v_pk_fma_f32 v[8:9], v[4:5], v[14:15], v[8:9]
	v_pk_fma_f32 v[4:5], v[2:3], v[16:17], v[6:7]
	v_cvt_pk_bf16_f32 v2, v10, v11
	v_cvt_pk_bf16_f32 v3, v12, v13
	v_cvt_pk_bf16_f32 v4, v4, v5
	v_cvt_pk_bf16_f32 v5, v8, v9
	ds_write_b128 v128, v[2:5]
	s_waitcnt lgkmcnt(0)
	s_barrier
	ds_read_b64_tr_b16 v[2:3], v129
	ds_read_b64_tr_b16 v[4:5], v129 offset:256
	ds_read_b128 v[6:9], v130
	s_waitcnt lgkmcnt(0)
	v_mfma_f32_32x32x16_bf16 v[50:65], v[2:5], v[6:9], 0
	ds_read_b128 v[6:9], v130 offset:8192
	s_waitcnt lgkmcnt(0)
	v_mfma_f32_32x32x16_bf16 v[34:49], v[2:5], v[6:9], 0
	ds_read_b128 v[6:9], v130 offset:16384
	s_waitcnt lgkmcnt(0)
	v_mfma_f32_32x32x16_bf16 v[18:33], v[2:5], v[6:9], 0
	ds_read_b128 v[6:9], v130 offset:24576
	ds_read_b64_tr_b16 v[148:149], v131
	ds_read_b64_tr_b16 v[150:151], v131 offset:256
	ds_read_b128 v[152:155], v132
	s_waitcnt lgkmcnt(0)
	v_mfma_f32_32x32x16_bf16 v[50:65], v[148:151], v[152:155], v[50:65]
	ds_read_b128 v[152:155], v132 offset:8192
	s_waitcnt lgkmcnt(0)
	v_mfma_f32_32x32x16_bf16 v[34:49], v[148:151], v[152:155], v[34:49]
	ds_read_b128 v[152:155], v132 offset:16384
	v_mfma_f32_32x32x16_bf16 v[2:17], v[2:5], v[6:9], 0
	s_waitcnt lgkmcnt(0)
	v_mfma_f32_32x32x16_bf16 v[18:33], v[148:151], v[152:155], v[18:33]
	ds_read_b128 v[152:155], v132 offset:24576
	s_waitcnt lgkmcnt(0)
	v_mfma_f32_32x32x16_bf16 v[2:17], v[148:151], v[152:155], v[2:17]
	ds_read_b64_tr_b16 v[148:149], v133
	ds_read_b64_tr_b16 v[150:151], v133 offset:256
	ds_read_b128 v[152:155], v134
	s_waitcnt lgkmcnt(0)
	v_mfma_f32_32x32x16_bf16 v[50:65], v[148:151], v[152:155], v[50:65]
	ds_read_b128 v[152:155], v134 offset:8192
	s_waitcnt lgkmcnt(0)
	v_mfma_f32_32x32x16_bf16 v[34:49], v[148:151], v[152:155], v[34:49]
	ds_read_b128 v[152:155], v134 offset:16384
	s_waitcnt lgkmcnt(0)
	v_mfma_f32_32x32x16_bf16 v[18:33], v[148:151], v[152:155], v[18:33]
	ds_read_b128 v[152:155], v134 offset:24576
	s_waitcnt lgkmcnt(0)
	v_mfma_f32_32x32x16_bf16 v[2:17], v[148:151], v[152:155], v[2:17]
	ds_read_b64_tr_b16 v[148:149], v135
	ds_read_b64_tr_b16 v[150:151], v135 offset:256
	ds_read_b128 v[152:155], v136
	s_waitcnt lgkmcnt(0)
	v_mfma_f32_32x32x16_bf16 v[50:65], v[148:151], v[152:155], v[50:65]
	ds_read_b128 v[152:155], v136 offset:8192
	s_waitcnt lgkmcnt(0)
	v_mfma_f32_32x32x16_bf16 v[34:49], v[148:151], v[152:155], v[34:49]
	ds_read_b128 v[152:155], v136 offset:16384
	s_waitcnt lgkmcnt(0)
	v_mfma_f32_32x32x16_bf16 v[18:33], v[148:151], v[152:155], v[18:33]
	ds_read_b128 v[152:155], v136 offset:24576
	s_waitcnt lgkmcnt(0)
	v_mfma_f32_32x32x16_bf16 v[2:17], v[148:151], v[152:155], v[2:17]
	ds_read_b64_tr_b16 v[148:149], v137
	ds_read_b64_tr_b16 v[150:151], v137 offset:256
	ds_read_b128 v[152:155], v138
	s_waitcnt lgkmcnt(0)
	v_mfma_f32_32x32x16_bf16 v[50:65], v[148:151], v[152:155], v[50:65]
	ds_read_b128 v[152:155], v138 offset:8192
	s_waitcnt lgkmcnt(0)
	v_mfma_f32_32x32x16_bf16 v[34:49], v[148:151], v[152:155], v[34:49]
	ds_read_b128 v[152:155], v138 offset:16384
	s_waitcnt lgkmcnt(0)
	v_mfma_f32_32x32x16_bf16 v[18:33], v[148:151], v[152:155], v[18:33]
	ds_read_b128 v[152:155], v138 offset:24576
	s_waitcnt lgkmcnt(0)
	v_mfma_f32_32x32x16_bf16 v[2:17], v[148:151], v[152:155], v[2:17]
	ds_read_b64_tr_b16 v[148:149], v139
	ds_read_b64_tr_b16 v[150:151], v139 offset:256
	ds_read_b128 v[152:155], v140
	s_waitcnt lgkmcnt(0)
	v_mfma_f32_32x32x16_bf16 v[50:65], v[148:151], v[152:155], v[50:65]
	ds_read_b128 v[152:155], v140 offset:8192
	s_waitcnt lgkmcnt(0)
	v_mfma_f32_32x32x16_bf16 v[34:49], v[148:151], v[152:155], v[34:49]
	ds_read_b128 v[152:155], v140 offset:16384
	s_waitcnt lgkmcnt(0)
	v_mfma_f32_32x32x16_bf16 v[18:33], v[148:151], v[152:155], v[18:33]
	ds_read_b128 v[152:155], v140 offset:24576
	s_waitcnt lgkmcnt(0)
	v_mfma_f32_32x32x16_bf16 v[2:17], v[148:151], v[152:155], v[2:17]
	ds_read_b64_tr_b16 v[148:149], v141
	ds_read_b64_tr_b16 v[150:151], v141 offset:256
	ds_read_b128 v[152:155], v142
	s_waitcnt lgkmcnt(0)
	v_mfma_f32_32x32x16_bf16 v[50:65], v[148:151], v[152:155], v[50:65]
	ds_read_b128 v[152:155], v142 offset:8192
	s_waitcnt lgkmcnt(0)
	v_mfma_f32_32x32x16_bf16 v[34:49], v[148:151], v[152:155], v[34:49]
	ds_read_b128 v[152:155], v142 offset:16384
	s_waitcnt lgkmcnt(0)
	v_mfma_f32_32x32x16_bf16 v[18:33], v[148:151], v[152:155], v[18:33]
	ds_read_b128 v[152:155], v142 offset:24576
	s_waitcnt lgkmcnt(0)
	v_mfma_f32_32x32x16_bf16 v[2:17], v[148:151], v[152:155], v[2:17]
	ds_read_b64_tr_b16 v[148:149], v143
	ds_read_b64_tr_b16 v[150:151], v143 offset:256
	ds_read_b128 v[152:155], v144
	s_waitcnt lgkmcnt(0)
	v_mfma_f32_32x32x16_bf16 v[50:65], v[148:151], v[152:155], v[50:65]
	ds_read_b128 v[152:155], v144 offset:8192
	s_waitcnt lgkmcnt(0)
	v_mfma_f32_32x32x16_bf16 v[34:49], v[148:151], v[152:155], v[34:49]
	ds_read_b128 v[152:155], v144 offset:16384
	s_waitcnt lgkmcnt(0)
	v_mfma_f32_32x32x16_bf16 v[18:33], v[148:151], v[152:155], v[18:33]
	ds_read_b128 v[152:155], v144 offset:24576
	s_waitcnt lgkmcnt(0)
	s_barrier
; #define LAS __attribute__((address_space(3)))
; __device__ __forceinline__ unsigned cvt_pk_bf16(float lo, float hi) { f32x2 v = {lo, hi}; bf16x2_t b = __builtin_convertvector(v, bf16x2_t); return __builtin_bit_cast(unsigned, b); }
; __device__ __forceinline__ float bf_lo(unsigned u) { return __uint_as_float(u << 16); }
; __device__ __forceinline__ float bf_hi(unsigned u) { return __uint_as_float(u & 0xffff0000u); }
; __device__ __forceinline__ void phase_spatial(const Args& a, LAS unsigned char* lds, int j, int nchunks) {
;     ...
; #pragma unroll
;         for (int pb = 0; pb < 4; ++pb) { const int p = 32 * pb + r32; const float bias = bs[g * 128 + p];
; #pragma unroll
;             for (int g4 = 0; g4 < 4; ++g4) { u32x2 w; w.x = cvt_pk_bf16(acc[pb][4 * g4] + bias, acc[pb][4 * g4 + 1] + bias); w.y = cvt_pk_bf16(acc[pb][4 * g4 + 2] + bias, acc[pb][4 * g4 + 3] + bias);
;                 *(LAS u32x2*)(vt + p * 520 + (32 * wid + 8 * g4 + 4 * hi) * 2) = w; } }
;         __syncthreads();
;         { u32x4 uu[8];
; #pragma unroll
;           for (int p8 = 0; p8 < 8; ++p8) { const int row = lrow + 16 * p8; uu[p8] = *(const u32x4*)(Z + (row0 + row) * SGUW + g * 256 + lch * 8); }
; #pragma unroll
;           for (int p8 = 0; p8 < 8; ++p8) { const int row = lrow + 16 * p8; const u32x2 s0 = *(const LAS u32x2*)(vt + row * 520 + lch * 16), s1 = *(const LAS u32x2*)(vt + row * 520 + lch * 16 + 8);
;               u32x4 o; o.x = cvt_pk_bf16(bf_lo(uu[p8].x) * bf_lo(s0.x), bf_hi(uu[p8].x) * bf_hi(s0.x)); o.y = cvt_pk_bf16(bf_lo(uu[p8].y) * bf_lo(s0.y), bf_hi(uu[p8].y) * bf_hi(s0.y));
;               o.z = cvt_pk_bf16(bf_lo(uu[p8].z) * bf_lo(s1.x), bf_hi(uu[p8].z) * bf_hi(s1.x)); o.w = cvt_pk_bf16(bf_lo(uu[p8].w) * bf_lo(s1.y), bf_hi(uu[p8].w) * bf_hi(s1.y));
;               *(u32x4*)(Z + (row0 + row) * SGUW + g * 256 + lch * 8) = o; } }
	v_mfma_f32_32x32x16_bf16 v[2:17], v[148:151], v[152:155], v[2:17]
	s_waitcnt vmcnt(0)
	v_mov_b32_e32 v148, v224
	s_waitcnt vmcnt(0)
	v_add_f32_e64 v50, v50, v148
	v_add_f32_e64 v51, v51, v148
	v_add_f32_e64 v52, v52, v148
	v_add_f32_e64 v53, v53, v148
	v_cvt_pk_bf16_f32 v50, v50, v51
	v_cvt_pk_bf16_f32 v51, v52, v53
	v_pk_add_f32 v[52:53], v[54:55], v[148:149] op_sel_hi:[1,0]
	v_pk_add_f32 v[54:55], v[56:57], v[148:149] op_sel_hi:[1,0]
	v_cvt_pk_bf16_f32 v52, v52, v53
	v_cvt_pk_bf16_f32 v53, v54, v55
	ds_write2_b64 v145, v[50:51], v[52:53] offset1:2
	v_pk_add_f32 v[50:51], v[58:59], v[148:149] op_sel_hi:[1,0]
	v_pk_add_f32 v[52:53], v[60:61], v[148:149] op_sel_hi:[1,0]
	v_cvt_pk_bf16_f32 v50, v50, v51
	v_cvt_pk_bf16_f32 v51, v52, v53
	v_pk_add_f32 v[52:53], v[62:63], v[148:149] op_sel_hi:[1,0]
	v_pk_add_f32 v[54:55], v[64:65], v[148:149] op_sel_hi:[1,0]
	v_cvt_pk_bf16_f32 v52, v52, v53
	v_cvt_pk_bf16_f32 v53, v54, v55
	ds_write2_b64 v145, v[50:51], v[52:53] offset0:4 offset1:6
	s_waitcnt vmcnt(0)
	v_mov_b32_e32 v50, v225
	s_waitcnt vmcnt(0)
	v_pk_add_f32 v[34:35], v[34:35], v[50:51] op_sel_hi:[1,0]
	v_pk_add_f32 v[36:37], v[36:37], v[50:51] op_sel_hi:[1,0]
	v_cvt_pk_bf16_f32 v34, v34, v35
	v_cvt_pk_bf16_f32 v35, v36, v37
	v_pk_add_f32 v[36:37], v[38:39], v[50:51] op_sel_hi:[1,0]
	v_pk_add_f32 v[38:39], v[40:41], v[50:51] op_sel_hi:[1,0]
	v_cvt_pk_bf16_f32 v36, v36, v37
	v_cvt_pk_bf16_f32 v37, v38, v39
	v_add_u32_e32 v40, 0x4000, v145
	ds_write2_b64 v40, v[34:35], v[36:37] offset0:32 offset1:34
	v_pk_add_f32 v[34:35], v[42:43], v[50:51] op_sel_hi:[1,0]
	v_pk_add_f32 v[36:37], v[44:45], v[50:51] op_sel_hi:[1,0]
	v_cvt_pk_bf16_f32 v34, v34, v35
	v_cvt_pk_bf16_f32 v35, v36, v37
	v_pk_add_f32 v[36:37], v[46:47], v[50:51] op_sel_hi:[1,0]
	v_pk_add_f32 v[38:39], v[48:49], v[50:51] op_sel_hi:[1,0]
	v_cvt_pk_bf16_f32 v36, v36, v37
	v_cvt_pk_bf16_f32 v37, v38, v39
	ds_write2_b64 v40, v[34:35], v[36:37] offset0:36 offset1:38
	s_waitcnt vmcnt(0)
	v_mov_b32_e32 v34, v226
	v_add_u32_e32 v48, v115, v116
	s_waitcnt vmcnt(0)
	v_pk_add_f32 v[18:19], v[18:19], v[34:35] op_sel_hi:[1,0]
	v_pk_add_f32 v[20:21], v[20:21], v[34:35] op_sel_hi:[1,0]
	v_cvt_pk_bf16_f32 v18, v18, v19
	v_cvt_pk_bf16_f32 v19, v20, v21
	v_pk_add_f32 v[20:21], v[22:23], v[34:35] op_sel_hi:[1,0]
	v_pk_add_f32 v[22:23], v[24:25], v[34:35] op_sel_hi:[1,0]
	v_cvt_pk_bf16_f32 v20, v20, v21
	v_cvt_pk_bf16_f32 v21, v22, v23
	v_add_u32_e32 v24, 0x8000, v145
	ds_write2_b64 v24, v[18:19], v[20:21] offset0:64 offset1:66
	v_pk_add_f32 v[18:19], v[26:27], v[34:35] op_sel_hi:[1,0]
	v_pk_add_f32 v[20:21], v[28:29], v[34:35] op_sel_hi:[1,0]
	v_cvt_pk_bf16_f32 v18, v18, v19
	v_cvt_pk_bf16_f32 v19, v20, v21
	v_pk_add_f32 v[20:21], v[30:31], v[34:35] op_sel_hi:[1,0]
	v_pk_add_f32 v[22:23], v[32:33], v[34:35] op_sel_hi:[1,0]
	v_cvt_pk_bf16_f32 v20, v20, v21
	v_cvt_pk_bf16_f32 v21, v22, v23
	ds_write2_b64 v24, v[18:19], v[20:21] offset0:68 offset1:70
	s_waitcnt vmcnt(0)
	v_mov_b32_e32 v18, v227
	s_waitcnt vmcnt(0)
	v_pk_add_f32 v[2:3], v[2:3], v[18:19] op_sel_hi:[1,0]
	v_pk_add_f32 v[4:5], v[4:5], v[18:19] op_sel_hi:[1,0]
	v_cvt_pk_bf16_f32 v2, v2, v3
	v_cvt_pk_bf16_f32 v3, v4, v5
	v_pk_add_f32 v[4:5], v[6:7], v[18:19] op_sel_hi:[1,0]
	v_pk_add_f32 v[6:7], v[8:9], v[18:19] op_sel_hi:[1,0]
	v_cvt_pk_bf16_f32 v4, v4, v5
	v_cvt_pk_bf16_f32 v5, v6, v7
	v_add_u32_e32 v8, 0xc000, v145
	ds_write2_b64 v8, v[2:3], v[4:5] offset0:96 offset1:98
	v_pk_add_f32 v[2:3], v[10:11], v[18:19] op_sel_hi:[1,0]
	v_pk_add_f32 v[4:5], v[12:13], v[18:19] op_sel_hi:[1,0]
	v_cvt_pk_bf16_f32 v2, v2, v3
	v_cvt_pk_bf16_f32 v3, v4, v5
	v_pk_add_f32 v[4:5], v[14:15], v[18:19] op_sel_hi:[1,0]
	v_pk_add_f32 v[6:7], v[16:17], v[18:19] op_sel_hi:[1,0]
	v_cvt_pk_bf16_f32 v4, v4, v5
	v_cvt_pk_bf16_f32 v5, v6, v7
	ds_write2_b64 v8, v[2:3], v[4:5] offset0:100 offset1:102
	v_lshl_add_u64 v[2:3], v[74:75], 0, s[0:1]
	v_lshl_add_u64 v[52:53], v[2:3], 0, v[98:99]
	s_waitcnt lgkmcnt(0)
	s_barrier
	global_load_dwordx4 v[44:47], v[52:53], off
	v_lshl_add_u64 v[42:43], v[2:3], 0, v[100:101]
	global_load_dwordx4 v[26:29], v[42:43], off
	v_lshl_add_u64 v[40:41], v[2:3], 0, v[102:103]
	global_load_dwordx4 v[22:25], v[40:41], off
	v_lshl_add_u64 v[38:39], v[2:3], 0, v[104:105]
	global_load_dwordx4 v[18:21], v[38:39], off
	v_lshl_add_u64 v[36:37], v[2:3], 0, v[106:107]
	global_load_dwordx4 v[14:17], v[36:37], off
	v_lshl_add_u64 v[34:35], v[2:3], 0, v[108:109]
	global_load_dwordx4 v[10:13], v[34:35], off
	ds_read2_b64 v[48:51], v48 offset1:1
	v_lshl_add_u64 v[32:33], v[2:3], 0, v[110:111]
	global_load_dwordx4 v[6:9], v[32:33], off
	v_lshl_add_u64 v[30:31], v[2:3], 0, v[112:113]
	global_load_dwordx4 v[2:5], v[30:31], off
	s_waitcnt lgkmcnt(0)
	v_lshlrev_b32_e32 v56, 16, v48
	v_and_b32_e32 v57, 0xffff0000, v48
	v_lshlrev_b32_e32 v48, 16, v49
	v_and_b32_e32 v49, 0xffff0000, v49
	s_waitcnt vmcnt(7)
	v_lshlrev_b32_e32 v54, 16, v44
	v_and_b32_e32 v55, 0xffff0000, v44
	v_pk_mul_f32 v[54:55], v[54:55], v[56:57]
	s_nop 0
	v_cvt_pk_bf16_f32 v44, v54, v55
	v_lshlrev_b32_e32 v54, 16, v45
	v_and_b32_e32 v55, 0xffff0000, v45
	v_pk_mul_f32 v[48:49], v[54:55], v[48:49]
	v_lshlrev_b32_e32 v54, 16, v50
	v_cvt_pk_bf16_f32 v45, v48, v49
	v_lshlrev_b32_e32 v48, 16, v46
	v_and_b32_e32 v49, 0xffff0000, v46
	v_and_b32_e32 v55, 0xffff0000, v50
	v_pk_mul_f32 v[48:49], v[48:49], v[54:55]
	v_lshlrev_b32_e32 v50, 16, v51
	v_cvt_pk_bf16_f32 v46, v48, v49
	v_lshlrev_b32_e32 v48, 16, v47
	v_and_b32_e32 v49, 0xffff0000, v47
	v_and_b32_e32 v51, 0xffff0000, v51
	v_pk_mul_f32 v[48:49], v[48:49], v[50:51]
	s_nop 0
	v_cvt_pk_bf16_f32 v47, v48, v49
	global_store_dwordx4 v[52:53], v[44:47], off
	ds_read2_b64 v[44:47], v146 offset1:1
	s_waitcnt vmcnt(7)
; #define LAS __attribute__((address_space(3)))
; __device__ __forceinline__ unsigned cvt_pk_bf16(float lo, float hi) { f32x2 v = {lo, hi}; bf16x2_t b = __builtin_convertvector(v, bf16x2_t); return __builtin_bit_cast(unsigned, b); }
; __device__ __forceinline__ float bf_lo(unsigned u) { return __uint_as_float(u << 16); }
; __device__ __forceinline__ float bf_hi(unsigned u) { return __uint_as_float(u & 0xffff0000u); }
; __device__ __forceinline__ void phase_spatial(const Args& a, LAS unsigned char* lds, int j, int nchunks) {
;     ...
;           for (int p8 = 0; p8 < 8; ++p8) { const int row = lrow + 16 * p8; uu[p8] = *(const u32x4*)(Z + (row0 + row) * SGUW + g * 256 + lch * 8); }
; #pragma unroll
;           for (int p8 = 0; p8 < 8; ++p8) { const int row = lrow + 16 * p8; const u32x2 s0 = *(const LAS u32x2*)(vt + row * 520 + lch * 16), s1 = *(const LAS u32x2*)(vt + row * 520 + lch * 16 + 8);
;               u32x4 o; o.x = cvt_pk_bf16(bf_lo(uu[p8].x) * bf_lo(s0.x), bf_hi(uu[p8].x) * bf_hi(s0.x)); o.y = cvt_pk_bf16(bf_lo(uu[p8].y) * bf_lo(s0.y), bf_hi(uu[p8].y) * bf_hi(s0.y));
;               o.z = cvt_pk_bf16(bf_lo(uu[p8].z) * bf_lo(s1.x), bf_hi(uu[p8].z) * bf_hi(s1.x)); o.w = cvt_pk_bf16(bf_lo(uu[p8].w) * bf_lo(s1.y), bf_hi(uu[p8].w) * bf_hi(s1.y));
;               *(u32x4*)(Z + (row0 + row) * SGUW + g * 256 + lch * 8) = o; } }
;         __syncthreads();
	v_lshlrev_b32_e32 v48, 16, v26
	v_and_b32_e32 v49, 0xffff0000, v26
	s_waitcnt lgkmcnt(0)
	v_lshlrev_b32_e32 v50, 16, v44
	v_and_b32_e32 v51, 0xffff0000, v44
	v_pk_mul_f32 v[48:49], v[48:49], v[50:51]
	v_lshlrev_b32_e32 v44, 16, v45
	v_cvt_pk_bf16_f32 v26, v48, v49
	v_lshlrev_b32_e32 v48, 16, v27
	v_and_b32_e32 v49, 0xffff0000, v27
	v_and_b32_e32 v45, 0xffff0000, v45
	v_pk_mul_f32 v[44:45], v[48:49], v[44:45]
	v_lshlrev_b32_e32 v48, 16, v46
	v_cvt_pk_bf16_f32 v27, v44, v45
	v_lshlrev_b32_e32 v44, 16, v28
	v_and_b32_e32 v45, 0xffff0000, v28
	v_and_b32_e32 v49, 0xffff0000, v46
	v_pk_mul_f32 v[44:45], v[44:45], v[48:49]
	v_lshlrev_b32_e32 v46, 16, v47
	v_cvt_pk_bf16_f32 v28, v44, v45
	v_lshlrev_b32_e32 v44, 16, v29
	v_and_b32_e32 v45, 0xffff0000, v29
	v_and_b32_e32 v47, 0xffff0000, v47
	v_pk_mul_f32 v[44:45], v[44:45], v[46:47]
	s_nop 0
	v_cvt_pk_bf16_f32 v29, v44, v45
	global_store_dwordx4 v[42:43], v[26:29], off
	s_waitcnt vmcnt(7)
	v_lshlrev_b32_e32 v42, 16, v22
	v_and_b32_e32 v43, 0xffff0000, v22
	v_add_u32_e32 v26, 0x2080, v146
	ds_read2_b64 v[26:29], v26 offset1:1
	s_waitcnt lgkmcnt(0)
	v_lshlrev_b32_e32 v44, 16, v26
	v_and_b32_e32 v45, 0xffff0000, v26
	v_pk_mul_f32 v[42:43], v[42:43], v[44:45]
	v_lshlrev_b32_e32 v26, 16, v27
	v_cvt_pk_bf16_f32 v22, v42, v43
	v_lshlrev_b32_e32 v42, 16, v23
	v_and_b32_e32 v43, 0xffff0000, v23
	v_and_b32_e32 v27, 0xffff0000, v27
	v_pk_mul_f32 v[26:27], v[42:43], v[26:27]
	v_lshlrev_b32_e32 v42, 16, v28
	v_cvt_pk_bf16_f32 v23, v26, v27
	v_lshlrev_b32_e32 v26, 16, v24
	v_and_b32_e32 v27, 0xffff0000, v24
	v_and_b32_e32 v43, 0xffff0000, v28
	v_pk_mul_f32 v[26:27], v[26:27], v[42:43]
	v_lshlrev_b32_e32 v28, 16, v29
	v_cvt_pk_bf16_f32 v24, v26, v27
	v_lshlrev_b32_e32 v26, 16, v25
	v_and_b32_e32 v27, 0xffff0000, v25
	v_and_b32_e32 v29, 0xffff0000, v29
	v_pk_mul_f32 v[26:27], v[26:27], v[28:29]
	s_nop 0
	v_cvt_pk_bf16_f32 v25, v26, v27
	global_store_dwordx4 v[40:41], v[22:25], off
	s_waitcnt vmcnt(7)
	v_lshlrev_b32_e32 v26, 16, v18
	v_and_b32_e32 v27, 0xffff0000, v18
	v_add_u32_e32 v22, 0x4100, v146
	ds_read2_b64 v[22:25], v22 offset1:1
	s_waitcnt lgkmcnt(0)
	v_lshlrev_b32_e32 v28, 16, v22
	v_and_b32_e32 v29, 0xffff0000, v22
	v_pk_mul_f32 v[26:27], v[26:27], v[28:29]
	v_lshlrev_b32_e32 v22, 16, v23
	v_cvt_pk_bf16_f32 v18, v26, v27
	v_lshlrev_b32_e32 v26, 16, v19
	v_and_b32_e32 v27, 0xffff0000, v19
	v_and_b32_e32 v23, 0xffff0000, v23
	v_pk_mul_f32 v[22:23], v[26:27], v[22:23]
	v_lshlrev_b32_e32 v26, 16, v24
	v_cvt_pk_bf16_f32 v19, v22, v23
	v_lshlrev_b32_e32 v22, 16, v20
	v_and_b32_e32 v23, 0xffff0000, v20
	v_and_b32_e32 v27, 0xffff0000, v24
	v_pk_mul_f32 v[22:23], v[22:23], v[26:27]
	v_lshlrev_b32_e32 v24, 16, v25
	v_cvt_pk_bf16_f32 v20, v22, v23
	v_lshlrev_b32_e32 v22, 16, v21
	v_and_b32_e32 v23, 0xffff0000, v21
	v_and_b32_e32 v25, 0xffff0000, v25
	v_pk_mul_f32 v[22:23], v[22:23], v[24:25]
	s_nop 0
	v_cvt_pk_bf16_f32 v21, v22, v23
	global_store_dwordx4 v[38:39], v[18:21], off
	s_waitcnt vmcnt(7)
	v_lshlrev_b32_e32 v22, 16, v14
	v_and_b32_e32 v23, 0xffff0000, v14
	v_add_u32_e32 v18, 0x6180, v146
	ds_read2_b64 v[18:21], v18 offset1:1
	s_waitcnt lgkmcnt(0)
	v_lshlrev_b32_e32 v24, 16, v18
	v_and_b32_e32 v25, 0xffff0000, v18
	v_pk_mul_f32 v[22:23], v[22:23], v[24:25]
	v_lshlrev_b32_e32 v18, 16, v19
	v_cvt_pk_bf16_f32 v14, v22, v23
	v_lshlrev_b32_e32 v22, 16, v15
	v_and_b32_e32 v23, 0xffff0000, v15
	v_and_b32_e32 v19, 0xffff0000, v19
	v_pk_mul_f32 v[18:19], v[22:23], v[18:19]
	v_lshlrev_b32_e32 v22, 16, v20
	v_cvt_pk_bf16_f32 v15, v18, v19
	v_lshlrev_b32_e32 v18, 16, v16
	v_and_b32_e32 v19, 0xffff0000, v16
	v_and_b32_e32 v23, 0xffff0000, v20
	v_pk_mul_f32 v[18:19], v[18:19], v[22:23]
	v_lshlrev_b32_e32 v20, 16, v21
	v_cvt_pk_bf16_f32 v16, v18, v19
	v_lshlrev_b32_e32 v18, 16, v17
	v_and_b32_e32 v19, 0xffff0000, v17
	v_and_b32_e32 v21, 0xffff0000, v21
	v_pk_mul_f32 v[18:19], v[18:19], v[20:21]
	s_nop 0
	v_cvt_pk_bf16_f32 v17, v18, v19
	global_store_dwordx4 v[36:37], v[14:17], off
	s_waitcnt vmcnt(7)
	v_lshlrev_b32_e32 v18, 16, v10
	v_and_b32_e32 v19, 0xffff0000, v10
	v_add_u32_e32 v14, 0x8200, v146
	ds_read2_b64 v[14:17], v14 offset1:1
	s_waitcnt lgkmcnt(0)
	v_lshlrev_b32_e32 v20, 16, v14
	v_and_b32_e32 v21, 0xffff0000, v14
	v_pk_mul_f32 v[18:19], v[18:19], v[20:21]
	v_lshlrev_b32_e32 v14, 16, v15
	v_cvt_pk_bf16_f32 v10, v18, v19
	v_lshlrev_b32_e32 v18, 16, v11
	v_and_b32_e32 v19, 0xffff0000, v11
	v_and_b32_e32 v15, 0xffff0000, v15
	v_pk_mul_f32 v[14:15], v[18:19], v[14:15]
	v_lshlrev_b32_e32 v18, 16, v16
	v_cvt_pk_bf16_f32 v11, v14, v15
	v_lshlrev_b32_e32 v14, 16, v12
	v_and_b32_e32 v15, 0xffff0000, v12
	v_and_b32_e32 v19, 0xffff0000, v16
	v_pk_mul_f32 v[14:15], v[14:15], v[18:19]
	v_lshlrev_b32_e32 v16, 16, v17
	v_cvt_pk_bf16_f32 v12, v14, v15
	v_lshlrev_b32_e32 v14, 16, v13
	v_and_b32_e32 v15, 0xffff0000, v13
	v_and_b32_e32 v17, 0xffff0000, v17
	v_pk_mul_f32 v[14:15], v[14:15], v[16:17]
	s_nop 0
	v_cvt_pk_bf16_f32 v13, v14, v15
	global_store_dwordx4 v[34:35], v[10:13], off
	s_waitcnt vmcnt(7)
	v_lshlrev_b32_e32 v14, 16, v6
	v_and_b32_e32 v15, 0xffff0000, v6
	v_add_u32_e32 v10, 0xa280, v146
	ds_read2_b64 v[10:13], v10 offset1:1
	s_waitcnt lgkmcnt(0)
	v_lshlrev_b32_e32 v16, 16, v10
	v_and_b32_e32 v17, 0xffff0000, v10
	v_pk_mul_f32 v[14:15], v[14:15], v[16:17]
	v_lshlrev_b32_e32 v10, 16, v11
	v_cvt_pk_bf16_f32 v6, v14, v15
	v_lshlrev_b32_e32 v14, 16, v7
	v_and_b32_e32 v15, 0xffff0000, v7
	v_and_b32_e32 v11, 0xffff0000, v11
	v_pk_mul_f32 v[10:11], v[14:15], v[10:11]
	v_lshlrev_b32_e32 v14, 16, v12
	v_cvt_pk_bf16_f32 v7, v10, v11
	v_lshlrev_b32_e32 v10, 16, v8
	v_and_b32_e32 v11, 0xffff0000, v8
	v_and_b32_e32 v15, 0xffff0000, v12
	v_pk_mul_f32 v[10:11], v[10:11], v[14:15]
	v_lshlrev_b32_e32 v12, 16, v13
	v_cvt_pk_bf16_f32 v8, v10, v11
	v_lshlrev_b32_e32 v10, 16, v9
	v_and_b32_e32 v11, 0xffff0000, v9
	v_and_b32_e32 v13, 0xffff0000, v13
	v_pk_mul_f32 v[10:11], v[10:11], v[12:13]
	s_nop 0
	v_cvt_pk_bf16_f32 v9, v10, v11
	global_store_dwordx4 v[32:33], v[6:9], off
	s_waitcnt vmcnt(7)
	v_lshlrev_b32_e32 v10, 16, v2
	v_and_b32_e32 v11, 0xffff0000, v2
	v_add_u32_e32 v6, 0xc300, v146
	ds_read2_b64 v[6:9], v6 offset1:1
	s_waitcnt lgkmcnt(0)
	v_lshlrev_b32_e32 v12, 16, v6
	v_and_b32_e32 v13, 0xffff0000, v6
	v_pk_mul_f32 v[10:11], v[10:11], v[12:13]
	v_lshlrev_b32_e32 v6, 16, v7
	v_cvt_pk_bf16_f32 v2, v10, v11
	v_lshlrev_b32_e32 v10, 16, v3
	v_and_b32_e32 v11, 0xffff0000, v3
	v_and_b32_e32 v7, 0xffff0000, v7
	v_pk_mul_f32 v[6:7], v[10:11], v[6:7]
	v_lshlrev_b32_e32 v10, 16, v8
	v_cvt_pk_bf16_f32 v3, v6, v7
	v_lshlrev_b32_e32 v6, 16, v4
	v_and_b32_e32 v7, 0xffff0000, v4
	v_and_b32_e32 v11, 0xffff0000, v8
	v_pk_mul_f32 v[6:7], v[6:7], v[10:11]
	v_lshlrev_b32_e32 v8, 16, v9
	v_cvt_pk_bf16_f32 v4, v6, v7
	v_lshlrev_b32_e32 v6, 16, v5
	v_and_b32_e32 v7, 0xffff0000, v5
	v_and_b32_e32 v9, 0xffff0000, v9
	v_pk_mul_f32 v[6:7], v[6:7], v[8:9]
	s_nop 0
	v_cvt_pk_bf16_f32 v5, v6, v7
	global_store_dwordx4 v[30:31], v[2:5], off
	s_barrier
	s_cbranch_scc1 .LBB0_254

.LBB0_298:
	v_add_co_u32_e32 v128, vcc, 0x30000, v14
	s_nop 1
	v_addc_co_u32_e32 v129, vcc, 0, v15, vcc
	global_load_dwordx4 v[152:155], v[14:15], off
	global_load_dwordx4 v[156:159], v[128:129], off
	s_cmpk_gt_u32 s0, 0x81
	s_cbranch_scc1 .Lat_e_nokw
	ds_write_b128 v227, v[144:147]
	ds_write_b128 v227, v[148:151] offset:4096
.Lat_e_nokw:
	s_and_b64 vcc, exec, s[38:39]
	s_cbranch_vccnz .LBB0_300
	v_add_u32_e32 v0, s11, v234
	ds_read_b64_tr_b16 v[128:129], v0
	ds_read_b64_tr_b16 v[130:131], v0 offset:512
	ds_read_b64_tr_b16 v[132:133], v0 offset:1024
	ds_read_b64_tr_b16 v[134:135], v0 offset:1536
	ds_read_b64_tr_b16 v[136:137], v0 offset:2048
	ds_read_b64_tr_b16 v[138:139], v0 offset:2560
	ds_read_b64_tr_b16 v[140:141], v0 offset:3072
	ds_read_b64_tr_b16 v[142:143], v0 offset:3584
	s_waitcnt lgkmcnt(6)
	v_mfma_f32_32x32x16_bf16 v[64:79], v[128:131], v[112:115], v[64:79]
	s_waitcnt lgkmcnt(4)
	v_mfma_f32_32x32x16_bf16 v[64:79], v[132:135], v[116:119], v[64:79]
	ds_read_b64_tr_b16 v[128:129], v0 offset:4096
	ds_read_b64_tr_b16 v[130:131], v0 offset:4608
	ds_read_b64_tr_b16 v[132:133], v0 offset:5120
	ds_read_b64_tr_b16 v[134:135], v0 offset:5632
	s_waitcnt lgkmcnt(6)
	v_mfma_f32_32x32x16_bf16 v[64:79], v[136:139], v[120:123], v[64:79]
	s_waitcnt lgkmcnt(4)
	v_mfma_f32_32x32x16_bf16 v[64:79], v[140:143], v[124:127], v[64:79]
	ds_read_b64_tr_b16 v[136:137], v0 offset:6144
	ds_read_b64_tr_b16 v[138:139], v0 offset:6656
	ds_read_b64_tr_b16 v[140:141], v0 offset:7168
	ds_read_b64_tr_b16 v[142:143], v0 offset:7680
	s_waitcnt lgkmcnt(6)
	v_mfma_f32_32x32x16_bf16 v[48:63], v[128:131], v[112:115], v[48:63]
	s_waitcnt lgkmcnt(4)
	v_mfma_f32_32x32x16_bf16 v[48:63], v[132:135], v[116:119], v[48:63]
	ds_read_b64_tr_b16 v[128:129], v0 offset:8192
	ds_read_b64_tr_b16 v[130:131], v0 offset:8704
	ds_read_b64_tr_b16 v[132:133], v0 offset:9216
	ds_read_b64_tr_b16 v[134:135], v0 offset:9728
	s_waitcnt lgkmcnt(6)
	v_mfma_f32_32x32x16_bf16 v[48:63], v[136:139], v[120:123], v[48:63]
	s_waitcnt lgkmcnt(4)
	v_mfma_f32_32x32x16_bf16 v[48:63], v[140:143], v[124:127], v[48:63]
	ds_read_b64_tr_b16 v[136:137], v0 offset:10240
	ds_read_b64_tr_b16 v[138:139], v0 offset:10752
	ds_read_b64_tr_b16 v[140:141], v0 offset:11264
	ds_read_b64_tr_b16 v[142:143], v0 offset:11776
	s_waitcnt lgkmcnt(6)
	v_mfma_f32_32x32x16_bf16 v[32:47], v[128:131], v[112:115], v[32:47]
	s_waitcnt lgkmcnt(4)
	v_mfma_f32_32x32x16_bf16 v[32:47], v[132:135], v[116:119], v[32:47]
	ds_read_b64_tr_b16 v[176:177], v0 offset:12288
	ds_read_b64_tr_b16 v[178:179], v0 offset:12800
	ds_read_b64_tr_b16 v[180:181], v0 offset:13312
	ds_read_b64_tr_b16 v[182:183], v0 offset:13824
	s_waitcnt lgkmcnt(6)
	v_mfma_f32_32x32x16_bf16 v[32:47], v[136:139], v[120:123], v[32:47]
	s_waitcnt lgkmcnt(4)
	v_mfma_f32_32x32x16_bf16 v[32:47], v[140:143], v[124:127], v[32:47]
	ds_read_b64_tr_b16 v[128:129], v0 offset:14336
	ds_read_b64_tr_b16 v[130:131], v0 offset:14848
	ds_read_b64_tr_b16 v[132:133], v0 offset:15360
	ds_read_b64_tr_b16 v[134:135], v0 offset:15872
	s_waitcnt lgkmcnt(6)
	v_mfma_f32_32x32x16_bf16 v[16:31], v[176:179], v[112:115], v[16:31]
	s_waitcnt lgkmcnt(4)
	v_mfma_f32_32x32x16_bf16 v[16:31], v[180:183], v[116:119], v[16:31]
	s_waitcnt lgkmcnt(2)
	v_mfma_f32_32x32x16_bf16 v[16:31], v[128:131], v[120:123], v[16:31]
	s_waitcnt lgkmcnt(0)
	v_mfma_f32_32x32x16_bf16 v[16:31], v[132:135], v[124:127], v[16:31]

.LBB0_306:
	s_add_i32 s57, s33, 0
	v_add_u32_e32 v218, s57, v226
	s_cmpk_gt_u32 s0, 0x7f
	s_waitcnt vmcnt(1)
	ds_write_b128 v218, v[152:155]
	s_waitcnt vmcnt(0)
	ds_write_b128 v218, v[156:159] offset:2048
	s_waitcnt lgkmcnt(0)
	s_barrier
	s_cbranch_scc1 .LBB0_320
	s_andn2_b64 vcc, exec, s[58:59]
	s_cbranch_vccnz .Lat_o_nokw1
	ds_write_b128 v227, v[10:13] offset:16384
	ds_write_b128 v227, v[184:187] offset:20480
.Lat_o_nokw1:
	v_mad_i64_i32 v[144:145], s[40:41], s64, v222, v[212:213]
	v_add_co_u32_e32 v148, vcc, 0x30000, v144
	s_nop 1
	v_addc_co_u32_e32 v149, vcc, 0, v145, vcc
	global_load_dwordx4 v[144:147], v[144:145], off
	s_nop 0
	global_load_dwordx4 v[148:151], v[148:149], off
	v_cndmask_b32_e64 v218, 0, 1, s[10:11]
	v_cmp_ne_u32_e64 s[40:41], 1, v218
	s_andn2_b64 vcc, exec, s[10:11]
	s_cbranch_vccz .LBB0_321

.LBB0_314:
	s_andn2_b64 vcc, exec, s[58:59]
	s_cbranch_vccnz .LBB0_316
.LBB0_316:
	s_add_i32 s10, s33, 0x4000
	s_cmp_lg_u32 s33, 0x10000
	s_cselect_b32 s10, s10, 0x8000
	s_and_b64 vcc, exec, s[40:41]
	s_cbranch_vccnz .LBB0_318
	v_add_u32_e32 v129, s10, v228
	s_waitcnt vmcnt(1)
	ds_write_b128 v129, v[152:155]
	s_waitcnt vmcnt(0)
	ds_write_b128 v129, v[156:159] offset:2048
.LBB0_318:
	s_add_i32 s0, s0, 2
	s_add_i32 s11, s10, 0x4000
	v_add_f32_e32 v0, v237, v0
	s_cmp_lg_u32 s10, 0x10000
	s_mov_b64 s[58:59], 0xc0000
	v_add_f32_e32 v237, v0, v128
	s_cselect_b32 s40, s11, 0x8000
	s_addk_i32 s64, 0x80
	v_lshl_add_u64 v[14:15], v[14:15], 0, s[58:59]
	s_and_b64 vcc, exec, s[34:35]
	s_waitcnt lgkmcnt(0)
	s_barrier
	s_cbranch_vccnz .LBB0_324
	s_mov_b32 s11, s33
	s_mov_b32 s33, s40
	s_cmpk_lt_u32 s0, 0x81
	s_cselect_b64 s[58:59], -1, 0
	s_cmpk_gt_u32 s0, 0x80
	s_cbranch_scc0 .LBB0_297
	s_branch .LBB0_298
.LBB0_320:
	s_andn2_b64 vcc, exec, s[58:59]
	s_cbranch_vccnz .Lat_o_nokw2
	ds_write_b128 v227, v[10:13] offset:16384
	ds_write_b128 v227, v[184:187] offset:20480
.Lat_o_nokw2:
	v_cndmask_b32_e64 v218, 0, 1, s[10:11]
	v_cmp_ne_u32_e64 s[40:41], 1, v218
	s_andn2_b64 vcc, exec, s[10:11]
	s_cbranch_vccnz .LBB0_308
